# adds: accumulator zeroing with 64-bit moves of inline 0, negm copies in flash A/C loops removed via out-of-place MFMA C operand
# speedup vs baseline: 1.0397x; 1.0007x over previous
;     __device__ bool next(int i, Unit& u) const { const int tl = (i >> 2) * G + c; if (tl >= nM * 4) return false; const int sub = i & 3; u.pm = sub * nM + (tl >> 2); u.pn = sub * 4 + (tl & 3); return true; }
; template <class Epi, class Sched, bool ALIGN_EPI = false, bool SP2 = false>
; __device__ __forceinline__ void gemm_phase(PG8_LAS unsigned char* lds, const Gemm g, const Sched& S, const Epi& E) {
;     ...
;     f32x4 acc[2][2][4][2];
; #pragma unroll
;     for (int a = 0; a < 2; ++a)
; #pragma unroll
;         for (int b = 0; b < 2; ++b)
; #pragma unroll
;             for (int m = 0; m < 4; ++m)
; #pragma unroll
;                 for (int n = 0; n < 2; ++n) acc[a][b][m][n] = (f32x4){0.f, 0.f, 0.f, 0.f};
;     ...
;         const bool has_next = S.next(ui + 1, nxt);
;         const char* nA = has_next ? (const char*)g.A + (size_t)nxt.pm * tstep : cA; const char* nB = has_next ? (const char*)g.Bt + (size_t)nxt.pn * tstep : cB;
;         for (int t = 0; t < nt; t += 2) {
;             const bool last = (t == nt - 2);
;             const char* a1 = cA + (size_t)(t + 1) * kstep;
;             const char* a2 = last ? nA : cA + (size_t)(t + 2) * kstep; const char* b2 = last ? nB : cB + (size_t)(t + 2) * kstep;
;             const char* a3 = a2 + kstep; const char* b3 = b2 + kstep;
.LBB0_277:
	s_ashr_i32 s35, s34, 31
	s_lshl_b64 s[8:9], s[34:35], 19
	s_add_u32 s42, s54, s8
	s_addc_u32 s43, s60, s9
	s_and_b64 s[8:9], s[38:39], exec
	s_cselect_b32 s7, s43, s49
	s_cselect_b32 s8, s42, s48
	s_ashr_i32 s29, s28, 31
	s_lshl_b64 s[44:45], s[28:29], 19
	s_add_u32 s44, s62, s44
	s_addc_u32 s45, s63, s45
	s_and_b64 s[68:69], s[38:39], exec
	s_cselect_b32 s9, s45, s47
	s_cselect_b32 s16, s44, s46
	s_add_u32 s29, s46, 0x100
	s_addc_u32 s35, s47, 0
	s_add_u32 s46, s48, 0x40080
	v_mov_b32_e32 v0, 0
	s_addc_u32 s47, s49, 0
	s_mov_b32 s41, -2
	v_mov_b32_e32 v1, 0
	v_mov_b64_e32 v[2:3], 0
	v_mov_b64_e32 v[4:5], 0
	v_mov_b64_e32 v[6:7], 0
	v_mov_b64_e32 v[8:9], 0
	v_mov_b64_e32 v[10:11], 0
	v_mov_b64_e32 v[12:13], 0
	v_mov_b64_e32 v[14:15], 0
	v_mov_b64_e32 v[16:17], 0
	v_mov_b64_e32 v[18:19], 0
	v_mov_b64_e32 v[20:21], 0
	v_mov_b64_e32 v[22:23], 0
	v_mov_b64_e32 v[24:25], 0
	v_mov_b64_e32 v[26:27], 0
	v_mov_b64_e32 v[28:29], 0
	v_mov_b64_e32 v[30:31], 0
	v_mov_b64_e32 v[32:33], 0
	v_mov_b64_e32 v[34:35], 0
	v_mov_b64_e32 v[36:37], 0
	v_mov_b64_e32 v[38:39], 0
	v_mov_b64_e32 v[40:41], 0
	v_mov_b64_e32 v[42:43], 0
	v_mov_b64_e32 v[44:45], 0
	v_mov_b64_e32 v[46:47], 0
	v_mov_b64_e32 v[48:49], 0
	v_mov_b64_e32 v[50:51], 0
	v_mov_b64_e32 v[52:53], 0
	v_mov_b64_e32 v[54:55], 0
	v_mov_b64_e32 v[56:57], 0
	v_mov_b64_e32 v[58:59], 0
	v_mov_b64_e32 v[60:61], 0
	v_mov_b64_e32 v[62:63], 0
	v_mov_b64_e32 v[64:65], 0
	v_mov_b64_e32 v[66:67], 0
	v_mov_b64_e32 v[68:69], 0
	v_mov_b64_e32 v[70:71], 0
	v_mov_b64_e32 v[72:73], 0
	v_mov_b64_e32 v[74:75], 0
	v_mov_b64_e32 v[76:77], 0
	v_mov_b64_e32 v[78:79], 0
	v_mov_b64_e32 v[80:81], 0
	v_mov_b64_e32 v[82:83], 0
	v_mov_b64_e32 v[84:85], 0
	v_mov_b64_e32 v[86:87], 0
	v_mov_b64_e32 v[88:89], 0
	v_mov_b64_e32 v[90:91], 0
	v_mov_b64_e32 v[92:93], 0
	v_mov_b64_e32 v[94:95], 0
	v_mov_b64_e32 v[96:97], 0
	v_mov_b64_e32 v[98:99], 0
	v_mov_b64_e32 v[100:101], 0
	v_mov_b64_e32 v[102:103], 0
	v_mov_b64_e32 v[104:105], 0
	v_mov_b64_e32 v[106:107], 0
	v_mov_b64_e32 v[108:109], 0
	v_mov_b64_e32 v[110:111], 0
	v_mov_b64_e32 v[112:113], 0
	v_mov_b64_e32 v[114:115], 0
	v_mov_b64_e32 v[116:117], 0
	v_mov_b64_e32 v[118:119], 0
	v_mov_b64_e32 v[120:121], 0
	v_mov_b64_e32 v[122:123], 0
	v_mov_b64_e32 v[124:125], 0
	v_mov_b64_e32 v[126:127], 0

; #define MFMA32(a, b, c) __builtin_amdgcn_mfma_f32_32x32x16_bf16((a), (b), (c), 0, 0, 0)
; template <int DQK, int NSUB, int MODE>
; __device__ __forceinline__ void flash_unit(LAS char* L, const bf16_t* Qp, int qpitch, const bf16_t* Kp, int kpitch, const bf16_t* Vp, int vpitch,
;                                            bf16_t* Op, int opitch, float lam, float oscale, const float* subln) {
;     ...
;         for (int s = 0; s < NSUB; ++s) {
;             f32x16 p0, p1;
; #pragma unroll
;             for (int d0 = 0; d0 < ND0; ++d0) { const bf16x8 k0 = *(const bf16x8*)(Kb + r32 * KPB + (s * DQK + 16 * d0 + 8 * hi) * 2); const bf16x8 k1 = *(const bf16x8*)(Kb + (32 + r32) * KPB + (s * DQK + 16 * d0 + 8 * hi) * 2);
;                 if (d0 == 0) { p0 = MFMA32(k0, qf[s][d0], negm[s]); p1 = MFMA32(k1, qf[s][d0], negm[s]); }
;                 else { p0 = MFMA32(k0, qf[s][d0], p0); p1 = MFMA32(k1, qf[s][d0], p1); } }
; #pragma unroll
;             for (int hf = 0; hf < 2; ++hf) {
;                 f32x16& ph = hf ? p1 : p0;
;                 float mx = fmaxf(ph[0], ph[1]);
; #pragma unroll
;                 for (int r = 2; r < 16; ++r) mx = fmaxf(mx, ph[r]);
;                 mx = fmaxf(mx, __shfl_xor(mx, 32));
;                 const bool first = (t == 0) && (hf == 0);
;                 if (first || __any(mx > 8.0f)) {
;                     const float dl = first ? mx : fmaxf(mx, 0.f); mref[s] += dl;
; #pragma unroll
;                     for (int r = 0; r < 16; ++r) { ph[r] -= dl; negm[s][r] = -mref[s]; }
;                     if (hf == 0) {
; #pragma unroll
;                         for (int r = 0; r < 16; ++r) p1[r] -= dl;
;                     }
;                     if (!first) { const float alpha = __builtin_amdgcn_exp2f(-dl); lrow[s] *= alpha;
; #pragma unroll
;                         for (int r = 0; r < 16; ++r) { o[s][0][r] *= alpha; o[s][1][r] *= alpha; } }
;                 }
.LBB0_579:
	s_and_b32 s8, s22, 1
	s_mul_i32 s9, s8, 0x2400
	v_add_u32_e32 v195, s9, v192
	ds_read_b128 v[96:99], v195
	ds_read_b128 v[100:103], v195 offset:32
	ds_read_b128 v[170:173], v195 offset:4608
	ds_read_b128 v[174:177], v195 offset:4640
	s_waitcnt lgkmcnt(0)
	v_mfma_f32_32x32x16_bf16 v[112:127], v[96:99], v[128:131], v[32:47]
	v_mfma_f32_32x32x16_bf16 v[112:127], v[100:103], v[132:135], v[112:127]
	s_nop 11
	v_max_f32_e32 v158, v113, v113
	v_max_f32_e32 v169, v112, v112
	v_mfma_f32_32x32x16_bf16 v[96:111], v[170:173], v[128:131], v[32:47]
	v_max_f32_e32 v158, v169, v158
	v_max3_f32 v158, v158, v114, v115
	v_max3_f32 v158, v158, v116, v117
	v_max3_f32 v158, v158, v118, v119
	v_max3_f32 v158, v158, v120, v121
	v_max3_f32 v158, v158, v122, v123
	v_max3_f32 v158, v158, v124, v125
	v_max3_f32 v158, v158, v126, v127
	v_mfma_f32_32x32x16_bf16 v[96:111], v[174:177], v[132:135], v[96:111]
	v_cmp_lt_f32_e32 vcc, s61, v158
	s_cbranch_vccz .LBB0_581
	ds_bpermute_b32 v169, v184, v158
	s_waitcnt lgkmcnt(0)
	v_max_f32_e32 v169, v169, v169
	v_max_f32_e32 v158, v158, v169
	v_max_f32_e32 v32, v158, v158
	v_max_f32_e32 v34, 0, v32
	v_exp_f32_e64 v36, -v34
	v_add_f32_e32 v159, v159, v34
	v_xor_b32_e32 v32, 0x80000000, v159
	v_pk_add_f32 v[112:113], v[112:113], v[34:35] op_sel_hi:[1,0] neg_lo:[0,1] neg_hi:[0,1]
	v_pk_add_f32 v[114:115], v[114:115], v[34:35] op_sel_hi:[1,0] neg_lo:[0,1] neg_hi:[0,1]
	v_pk_add_f32 v[116:117], v[116:117], v[34:35] op_sel_hi:[1,0] neg_lo:[0,1] neg_hi:[0,1]
	v_pk_add_f32 v[118:119], v[118:119], v[34:35] op_sel_hi:[1,0] neg_lo:[0,1] neg_hi:[0,1]
	v_pk_add_f32 v[120:121], v[120:121], v[34:35] op_sel_hi:[1,0] neg_lo:[0,1] neg_hi:[0,1]
	v_pk_add_f32 v[122:123], v[122:123], v[34:35] op_sel_hi:[1,0] neg_lo:[0,1] neg_hi:[0,1]
	v_pk_add_f32 v[124:125], v[124:125], v[34:35] op_sel_hi:[1,0] neg_lo:[0,1] neg_hi:[0,1]
	v_pk_add_f32 v[126:127], v[126:127], v[34:35] op_sel_hi:[1,0] neg_lo:[0,1] neg_hi:[0,1]
	v_sub_f32_e32 v111, v111, v34
	v_sub_f32_e32 v110, v110, v34
	v_sub_f32_e32 v109, v109, v34
	v_sub_f32_e32 v108, v108, v34
	v_sub_f32_e32 v107, v107, v34
	v_sub_f32_e32 v106, v106, v34
	v_sub_f32_e32 v105, v105, v34
	v_sub_f32_e32 v104, v104, v34
	v_sub_f32_e32 v103, v103, v34
	v_sub_f32_e32 v102, v102, v34
	v_sub_f32_e32 v101, v101, v34
	v_sub_f32_e32 v100, v100, v34
	v_sub_f32_e32 v99, v99, v34
	v_sub_f32_e32 v98, v98, v34
	v_sub_f32_e32 v97, v97, v34
	v_sub_f32_e32 v96, v96, v34
	v_pk_mul_f32 v[14:15], v[14:15], v[36:37] op_sel_hi:[1,0]
	v_pk_mul_f32 v[12:13], v[12:13], v[36:37] op_sel_hi:[1,0]
	v_pk_mul_f32 v[10:11], v[10:11], v[36:37] op_sel_hi:[1,0]
	v_pk_mul_f32 v[8:9], v[8:9], v[36:37] op_sel_hi:[1,0]
	v_pk_mul_f32 v[6:7], v[6:7], v[36:37] op_sel_hi:[1,0]
	v_pk_mul_f32 v[4:5], v[4:5], v[36:37] op_sel_hi:[1,0]
	v_pk_mul_f32 v[2:3], v[2:3], v[36:37] op_sel_hi:[1,0]
	v_pk_mul_f32 v[0:1], v[0:1], v[36:37] op_sel_hi:[1,0]
	v_pk_mul_f32 v[30:31], v[30:31], v[36:37] op_sel_hi:[1,0]
	v_pk_mul_f32 v[28:29], v[28:29], v[36:37] op_sel_hi:[1,0]
	v_pk_mul_f32 v[26:27], v[26:27], v[36:37] op_sel_hi:[1,0]
	v_pk_mul_f32 v[24:25], v[24:25], v[36:37] op_sel_hi:[1,0]
	v_pk_mul_f32 v[22:23], v[22:23], v[36:37] op_sel_hi:[1,0]
	v_pk_mul_f32 v[20:21], v[20:21], v[36:37] op_sel_hi:[1,0]
	v_pk_mul_f32 v[18:19], v[18:19], v[36:37] op_sel_hi:[1,0]
	v_pk_mul_f32 v[16:17], v[16:17], v[36:37] op_sel_hi:[1,0]
	v_mul_f32_e32 v168, v168, v36
	v_mov_b32_e32 v33, v32
	v_mov_b32_e32 v34, v32
	v_mov_b32_e32 v35, v32
	v_mov_b32_e32 v36, v32
	v_mov_b32_e32 v37, v32
	v_mov_b32_e32 v38, v32
	v_mov_b32_e32 v39, v32
	v_mov_b32_e32 v40, v32
	v_mov_b32_e32 v41, v32
	v_mov_b32_e32 v42, v32
	v_mov_b32_e32 v43, v32
	v_mov_b32_e32 v44, v32
	v_mov_b32_e32 v45, v32
	v_mov_b32_e32 v46, v32
	v_mov_b32_e32 v47, v32

; __device__ __forceinline__ unsigned cvt_pk_bf16(float lo, float hi) { typedef float f2 __attribute__((ext_vector_type(2))); typedef __bf16 b2 __attribute__((ext_vector_type(2))); f2 v = {lo, hi}; b2 b = __builtin_convertvector(v, b2); return __builtin_bit_cast(unsigned, b); }
; __device__ __forceinline__ v4i16_t vtr(LAS const char* p) { return __builtin_amdgcn_ds_read_tr16_b64_v4i16((LAS v4i16_t*)p); }
; template <int DQK, int NSUB, int MODE>
; __device__ __forceinline__ void flash_unit(LAS char* L, const bf16_t* Qp, int qpitch, const bf16_t* Kp, int kpitch, const bf16_t* Vp, int vpitch,
;                                            bf16_t* Op, int opitch, float lam, float oscale, const float* subln) {
;     ...
;         for (int s = 0; s < NSUB; ++s) {
;             f32x16 p0, p1;
; #pragma unroll
;             for (int d0 = 0; d0 < ND0; ++d0) { const bf16x8 k0 = *(const bf16x8*)(Kb + r32 * KPB + (s * DQK + 16 * d0 + 8 * hi) * 2); const bf16x8 k1 = *(const bf16x8*)(Kb + (32 + r32) * KPB + (s * DQK + 16 * d0 + 8 * hi) * 2);
;                 if (d0 == 0) { p0 = MFMA32(k0, qf[s][d0], negm[s]); p1 = MFMA32(k1, qf[s][d0], negm[s]); }
;                 else { p0 = MFMA32(k0, qf[s][d0], p0); p1 = MFMA32(k1, qf[s][d0], p1); } }
;     ...
; #pragma unroll
;                 for (int r = 0; r < 16; ++r) ph[r] = __builtin_amdgcn_exp2f(ph[r]);
;                 { typedef float f32x2_ __attribute__((ext_vector_type(2))); f32x2_ r2 = {ph[0], ph[1]};
; #pragma unroll
;                   for (int r = 2; r < 16; r += 2) r2 += (f32x2_){ph[r], ph[r + 1]};
;                   lrow[s] += r2[0] + r2[1]; }
;                 bf16x8 pf[2];
; #pragma unroll
;                 for (int k2 = 0; k2 < 2; ++k2) { u32x4 w;
; #pragma unroll
;                     for (int e = 0; e < 4; ++e) w[e] = cvt_pk_bf16(ph[8 * k2 + 2 * e], ph[8 * k2 + 2 * e + 1]);
;                     pf[k2] = __builtin_bit_cast(bf16x8, w); }
; #pragma unroll
;                 for (int db = 0; db < 2; ++db)
; #pragma unroll
;                     for (int k2 = 0; k2 < 2; ++k2) { const int ks = 2 * hf + k2; const v4i16_t lo = vtr(Vb + (16 * ks) * VPB + db * 64), hh = vtr(Vb + (16 * ks + 8) * VPB + db * 64);
;                         const bf16x8 vf = {lo[0], lo[1], lo[2], lo[3], hh[0], hh[1], hh[2], hh[3]};
;                         o[s][db] = MFMA32(vf, pf[k2], o[s][db]); }
.LBB0_583:
	v_exp_f32_e32 v168, v96
	v_exp_f32_e32 v169, v97
	v_exp_f32_e32 v170, v98
	v_exp_f32_e32 v171, v99
	v_exp_f32_e32 v172, v100
	v_exp_f32_e32 v173, v101
	v_exp_f32_e32 v174, v102
	v_exp_f32_e32 v175, v103
	v_exp_f32_e32 v176, v104
	v_exp_f32_e32 v177, v105
	v_exp_f32_e32 v178, v106
	v_exp_f32_e32 v179, v107
	ds_read_b64_tr_b16 v[104:105], v158 offset:23040
	ds_read_b64_tr_b16 v[106:107], v158 offset:24192
	v_cvt_pk_bf16_f32 v96, v168, v169
	v_cvt_pk_bf16_f32 v97, v170, v171
	v_cvt_pk_bf16_f32 v98, v172, v173
	v_cvt_pk_bf16_f32 v99, v174, v175
	v_exp_f32_e32 v180, v108
	v_exp_f32_e32 v181, v109
	s_waitcnt lgkmcnt(0)
	v_mfma_f32_32x32x16_bf16 v[0:15], v[104:107], v[96:99], v[0:15]
	v_exp_f32_e32 v182, v110
	v_exp_f32_e32 v183, v111
	ds_read_b64_tr_b16 v[104:105], v158 offset:25344
	ds_read_b64_tr_b16 v[106:107], v158 offset:26496
	v_cvt_pk_bf16_f32 v100, v176, v177
	v_cvt_pk_bf16_f32 v101, v178, v179
	v_cvt_pk_bf16_f32 v102, v180, v181
	v_cvt_pk_bf16_f32 v103, v182, v183
	s_waitcnt lgkmcnt(0)
	s_nop 0
	v_mfma_f32_32x32x16_bf16 v[0:15], v[104:107], v[100:103], v[0:15]
	ds_read_b64_tr_b16 v[104:105], v158 offset:23104
	ds_read_b64_tr_b16 v[106:107], v158 offset:24256
	s_waitcnt lgkmcnt(0)
	v_mfma_f32_32x32x16_bf16 v[16:31], v[104:107], v[96:99], v[16:31]
	ds_read_b64_tr_b16 v[96:97], v158 offset:25408
	ds_read_b64_tr_b16 v[98:99], v158 offset:26560
	s_waitcnt lgkmcnt(0)
	v_mfma_f32_32x32x16_bf16 v[16:31], v[96:99], v[100:103], v[16:31]
	ds_read_b128 v[196:199], v195 offset:4672
	ds_read_b128 v[96:99], v195 offset:64
	ds_read_b128 v[200:203], v195 offset:96
	s_waitcnt lgkmcnt(0)
	v_mfma_f32_32x32x16_bf16 v[112:127], v[96:99], v[136:139], v[80:95]
	v_mfma_f32_32x32x16_bf16 v[112:127], v[200:203], v[140:143], v[112:127]
	s_nop 0
	v_mfma_f32_32x32x16_bf16 v[96:111], v[196:199], v[136:139], v[80:95]
	ds_read_b128 v[196:199], v195 offset:4704
	s_nop 8
	v_max_f32_e32 v195, v113, v113
	s_waitcnt lgkmcnt(0)
	v_mfma_f32_32x32x16_bf16 v[96:111], v[196:199], v[140:143], v[96:111]
	v_max_f32_e32 v196, v112, v112
	v_max_f32_e32 v195, v196, v195
	v_max3_f32 v195, v195, v114, v115
	v_max3_f32 v195, v195, v116, v117
	v_max3_f32 v195, v195, v118, v119
	v_max3_f32 v195, v195, v120, v121
	v_max3_f32 v195, v195, v122, v123
	v_max3_f32 v195, v195, v124, v125
	v_max3_f32 v195, v195, v126, v127
	v_cmp_lt_f32_e32 vcc, s61, v195
	s_cbranch_vccz .LBB0_585
	ds_bpermute_b32 v196, v184, v195
	s_waitcnt lgkmcnt(0)
	v_max_f32_e32 v196, v196, v196
	v_max_f32_e32 v195, v195, v196
	v_max_f32_e32 v80, v195, v195
	v_max_f32_e32 v82, 0, v80
	v_exp_f32_e64 v84, -v82
	v_add_f32_e32 v161, v161, v82
	v_xor_b32_e32 v80, 0x80000000, v161
	v_pk_add_f32 v[112:113], v[112:113], v[82:83] op_sel_hi:[1,0] neg_lo:[0,1] neg_hi:[0,1]
	v_pk_add_f32 v[114:115], v[114:115], v[82:83] op_sel_hi:[1,0] neg_lo:[0,1] neg_hi:[0,1]
	v_pk_add_f32 v[116:117], v[116:117], v[82:83] op_sel_hi:[1,0] neg_lo:[0,1] neg_hi:[0,1]
	v_pk_add_f32 v[118:119], v[118:119], v[82:83] op_sel_hi:[1,0] neg_lo:[0,1] neg_hi:[0,1]
	v_pk_add_f32 v[120:121], v[120:121], v[82:83] op_sel_hi:[1,0] neg_lo:[0,1] neg_hi:[0,1]
	v_pk_add_f32 v[122:123], v[122:123], v[82:83] op_sel_hi:[1,0] neg_lo:[0,1] neg_hi:[0,1]
	v_pk_add_f32 v[124:125], v[124:125], v[82:83] op_sel_hi:[1,0] neg_lo:[0,1] neg_hi:[0,1]
	v_pk_add_f32 v[126:127], v[126:127], v[82:83] op_sel_hi:[1,0] neg_lo:[0,1] neg_hi:[0,1]
	v_sub_f32_e32 v111, v111, v82
	v_sub_f32_e32 v110, v110, v82
	v_sub_f32_e32 v109, v109, v82
	v_sub_f32_e32 v108, v108, v82
	v_sub_f32_e32 v107, v107, v82
	v_sub_f32_e32 v106, v106, v82
	v_sub_f32_e32 v105, v105, v82
	v_sub_f32_e32 v104, v104, v82
	v_sub_f32_e32 v103, v103, v82
	v_sub_f32_e32 v102, v102, v82
	v_sub_f32_e32 v101, v101, v82
	v_sub_f32_e32 v100, v100, v82
	v_sub_f32_e32 v99, v99, v82
	v_sub_f32_e32 v98, v98, v82
	v_sub_f32_e32 v97, v97, v82
	v_sub_f32_e32 v96, v96, v82
	v_pk_mul_f32 v[62:63], v[62:63], v[84:85] op_sel_hi:[1,0]
	v_pk_mul_f32 v[60:61], v[60:61], v[84:85] op_sel_hi:[1,0]
	v_pk_mul_f32 v[58:59], v[58:59], v[84:85] op_sel_hi:[1,0]
	v_pk_mul_f32 v[56:57], v[56:57], v[84:85] op_sel_hi:[1,0]
	v_pk_mul_f32 v[54:55], v[54:55], v[84:85] op_sel_hi:[1,0]
	v_pk_mul_f32 v[52:53], v[52:53], v[84:85] op_sel_hi:[1,0]
	v_pk_mul_f32 v[50:51], v[50:51], v[84:85] op_sel_hi:[1,0]
	v_pk_mul_f32 v[48:49], v[48:49], v[84:85] op_sel_hi:[1,0]
	v_pk_mul_f32 v[78:79], v[78:79], v[84:85] op_sel_hi:[1,0]
	v_pk_mul_f32 v[76:77], v[76:77], v[84:85] op_sel_hi:[1,0]
	v_pk_mul_f32 v[74:75], v[74:75], v[84:85] op_sel_hi:[1,0]
	v_pk_mul_f32 v[72:73], v[72:73], v[84:85] op_sel_hi:[1,0]
	v_pk_mul_f32 v[70:71], v[70:71], v[84:85] op_sel_hi:[1,0]
	v_pk_mul_f32 v[68:69], v[68:69], v[84:85] op_sel_hi:[1,0]
	v_pk_mul_f32 v[66:67], v[66:67], v[84:85] op_sel_hi:[1,0]
	v_pk_mul_f32 v[64:65], v[64:65], v[84:85] op_sel_hi:[1,0]
	v_mul_f32_e32 v160, v160, v84
	v_mov_b32_e32 v81, v80
	v_mov_b32_e32 v82, v80
	v_mov_b32_e32 v83, v80
	v_mov_b32_e32 v84, v80
	v_mov_b32_e32 v85, v80
	v_mov_b32_e32 v86, v80
	v_mov_b32_e32 v87, v80
	v_mov_b32_e32 v88, v80
	v_mov_b32_e32 v89, v80
	v_mov_b32_e32 v90, v80
	v_mov_b32_e32 v91, v80
	v_mov_b32_e32 v92, v80
	v_mov_b32_e32 v93, v80
	v_mov_b32_e32 v94, v80
	v_mov_b32_e32 v95, v80

; #define MFMA32(a, b, c) __builtin_amdgcn_mfma_f32_32x32x16_bf16((a), (b), (c), 0, 0, 0)
; template <int DQK, int NSUB, int MODE>
; __device__ __forceinline__ void flash_unit(LAS char* L, const bf16_t* Qp, int qpitch, const bf16_t* Kp, int kpitch, const bf16_t* Vp, int vpitch,
;                                            bf16_t* Op, int opitch, float lam, float oscale, const float* subln) {
;     ...
;         for (int s = 0; s < NSUB; ++s) {
;             f32x16 p0, p1;
; #pragma unroll
;             for (int d0 = 0; d0 < ND0; ++d0) { const bf16x8 k0 = *(const bf16x8*)(Kb + r32 * KPB + (s * DQK + 16 * d0 + 8 * hi) * 2); const bf16x8 k1 = *(const bf16x8*)(Kb + (32 + r32) * KPB + (s * DQK + 16 * d0 + 8 * hi) * 2);
;                 if (d0 == 0) { p0 = MFMA32(k0, qf[s][d0], negm[s]); p1 = MFMA32(k1, qf[s][d0], negm[s]); }
;                 else { p0 = MFMA32(k0, qf[s][d0], p0); p1 = MFMA32(k1, qf[s][d0], p1); } }
; #pragma unroll
;             for (int hf = 0; hf < 2; ++hf) {
;                 f32x16& ph = hf ? p1 : p0;
;                 float mx = fmaxf(ph[0], ph[1]);
; #pragma unroll
;                 for (int r = 2; r < 16; ++r) mx = fmaxf(mx, ph[r]);
;                 mx = fmaxf(mx, __shfl_xor(mx, 32));
;                 const bool first = (t == 0) && (hf == 0);
;                 if (first || __any(mx > 8.0f)) {
;                     const float dl = first ? mx : fmaxf(mx, 0.f); mref[s] += dl;
; #pragma unroll
;                     for (int r = 0; r < 16; ++r) { ph[r] -= dl; negm[s][r] = -mref[s]; }
;                     if (hf == 0) {
; #pragma unroll
;                         for (int r = 0; r < 16; ++r) p1[r] -= dl;
;                     }
;                     if (!first) { const float alpha = __builtin_amdgcn_exp2f(-dl); lrow[s] *= alpha;
; #pragma unroll
;                         for (int r = 0; r < 16; ++r) { o[s][0][r] *= alpha; o[s][1][r] *= alpha; } }
;                 }
.LBB0_612:
	s_and_b32 s8, s21, 1
	s_mul_i32 s9, s8, 0x3400
	v_add_u32_e32 v140, s9, v131
	ds_read_b128 v[132:135], v140 offset:6656
	ds_read_b128 v[48:51], v140
	ds_read_b128 v[136:139], v140 offset:32
	s_waitcnt lgkmcnt(0)
	v_mfma_f32_32x32x16_bf16 v[64:79], v[48:51], v[100:103], v[32:47]
	v_mfma_f32_32x32x16_bf16 v[64:79], v[136:139], v[80:83], v[64:79]
	s_nop 0
	v_mfma_f32_32x32x16_bf16 v[48:63], v[132:135], v[100:103], v[32:47]
	ds_read_b128 v[132:135], v140 offset:6688
	s_waitcnt lgkmcnt(0)
	v_mfma_f32_32x32x16_bf16 v[48:63], v[132:135], v[80:83], v[48:63]
	ds_read_b128 v[132:135], v140 offset:6720
	ds_read_b128 v[136:139], v140 offset:64
	s_waitcnt lgkmcnt(0)
	v_mfma_f32_32x32x16_bf16 v[64:79], v[136:139], v[84:87], v[64:79]
	v_mfma_f32_32x32x16_bf16 v[48:63], v[132:135], v[84:87], v[48:63]
	ds_read_b128 v[132:135], v140 offset:6752
	ds_read_b128 v[136:139], v140 offset:96
	s_waitcnt lgkmcnt(0)
	v_mfma_f32_32x32x16_bf16 v[64:79], v[136:139], v[88:91], v[64:79]
	v_mfma_f32_32x32x16_bf16 v[48:63], v[132:135], v[88:91], v[48:63]
	ds_read_b128 v[132:135], v140 offset:6784
	ds_read_b128 v[136:139], v140 offset:128
	s_waitcnt lgkmcnt(0)
	v_mfma_f32_32x32x16_bf16 v[64:79], v[136:139], v[92:95], v[64:79]
	v_mfma_f32_32x32x16_bf16 v[48:63], v[132:135], v[92:95], v[48:63]
	ds_read_b128 v[132:135], v140 offset:6816
	ds_read_b128 v[136:139], v140 offset:160
	s_waitcnt lgkmcnt(0)
	v_mfma_f32_32x32x16_bf16 v[64:79], v[136:139], v[96:99], v[64:79]
	v_mfma_f32_32x32x16_bf16 v[48:63], v[132:135], v[96:99], v[48:63]
	s_nop 10
	v_max_f32_e32 v132, v65, v65
	v_max_f32_e32 v133, v64, v64
	v_max_f32_e32 v132, v133, v132
	v_max3_f32 v132, v132, v66, v67
	v_max3_f32 v132, v132, v68, v69
	v_max3_f32 v132, v132, v70, v71
	v_max3_f32 v132, v132, v72, v73
	v_max3_f32 v132, v132, v74, v75
	v_max3_f32 v132, v132, v76, v77
	v_max3_f32 v132, v132, v78, v79
	v_cmp_lt_f32_e32 vcc, s61, v132
	s_cbranch_vccz .LBB0_614
	ds_bpermute_b32 v133, v184, v132
	s_waitcnt lgkmcnt(0)
	v_max_f32_e32 v133, v133, v133
	v_max_f32_e32 v132, v132, v133
	v_max_f32_e32 v32, v132, v132
	v_max_f32_e32 v33, 0, v32
	v_exp_f32_e64 v34, -v33
	v_add_f32_e32 v119, v119, v33
	v_xor_b32_e32 v32, 0x80000000, v119
	v_sub_f32_e32 v79, v79, v33
	v_sub_f32_e32 v78, v78, v33
	v_sub_f32_e32 v77, v77, v33
	v_sub_f32_e32 v76, v76, v33
	v_sub_f32_e32 v75, v75, v33
	v_sub_f32_e32 v74, v74, v33
	v_sub_f32_e32 v73, v73, v33
	v_sub_f32_e32 v72, v72, v33
	v_sub_f32_e32 v71, v71, v33
	v_sub_f32_e32 v70, v70, v33
	v_sub_f32_e32 v69, v69, v33
	v_sub_f32_e32 v68, v68, v33
	v_sub_f32_e32 v67, v67, v33
	v_sub_f32_e32 v66, v66, v33
	v_sub_f32_e32 v65, v65, v33
	v_sub_f32_e32 v64, v64, v33
	v_sub_f32_e32 v63, v63, v33
	v_sub_f32_e32 v62, v62, v33
	v_sub_f32_e32 v61, v61, v33
	v_sub_f32_e32 v60, v60, v33
	v_sub_f32_e32 v59, v59, v33
	v_sub_f32_e32 v58, v58, v33
	v_sub_f32_e32 v57, v57, v33
	v_sub_f32_e32 v56, v56, v33
	v_sub_f32_e32 v55, v55, v33
	v_sub_f32_e32 v54, v54, v33
	v_sub_f32_e32 v53, v53, v33
	v_sub_f32_e32 v52, v52, v33
	v_sub_f32_e32 v51, v51, v33
	v_sub_f32_e32 v50, v50, v33
	v_sub_f32_e32 v49, v49, v33
	v_sub_f32_e32 v48, v48, v33
	v_pk_mul_f32 v[30:31], v[30:31], v[34:35] op_sel_hi:[1,0]
	v_pk_mul_f32 v[28:29], v[28:29], v[34:35] op_sel_hi:[1,0]
	v_pk_mul_f32 v[26:27], v[26:27], v[34:35] op_sel_hi:[1,0]
	v_pk_mul_f32 v[24:25], v[24:25], v[34:35] op_sel_hi:[1,0]
	v_pk_mul_f32 v[22:23], v[22:23], v[34:35] op_sel_hi:[1,0]
	v_pk_mul_f32 v[20:21], v[20:21], v[34:35] op_sel_hi:[1,0]
	v_pk_mul_f32 v[18:19], v[18:19], v[34:35] op_sel_hi:[1,0]
	v_pk_mul_f32 v[16:17], v[16:17], v[34:35] op_sel_hi:[1,0]
	v_pk_mul_f32 v[14:15], v[14:15], v[34:35] op_sel_hi:[1,0]
	v_pk_mul_f32 v[12:13], v[12:13], v[34:35] op_sel_hi:[1,0]
	v_pk_mul_f32 v[10:11], v[10:11], v[34:35] op_sel_hi:[1,0]
	v_pk_mul_f32 v[8:9], v[8:9], v[34:35] op_sel_hi:[1,0]
	v_pk_mul_f32 v[6:7], v[6:7], v[34:35] op_sel_hi:[1,0]
	v_pk_mul_f32 v[4:5], v[4:5], v[34:35] op_sel_hi:[1,0]
	v_pk_mul_f32 v[2:3], v[2:3], v[34:35] op_sel_hi:[1,0]
	v_pk_mul_f32 v[0:1], v[0:1], v[34:35] op_sel_hi:[1,0]
	v_mul_f32_e32 v118, v118, v34
	v_mov_b32_e32 v33, v32
	v_mov_b32_e32 v34, v32
	v_mov_b32_e32 v35, v32
	v_mov_b32_e32 v36, v32
	v_mov_b32_e32 v37, v32
	v_mov_b32_e32 v38, v32
	v_mov_b32_e32 v39, v32
	v_mov_b32_e32 v40, v32
	v_mov_b32_e32 v41, v32
	v_mov_b32_e32 v42, v32
	v_mov_b32_e32 v43, v32
	v_mov_b32_e32 v44, v32
	v_mov_b32_e32 v45, v32
	v_mov_b32_e32 v46, v32
	v_mov_b32_e32 v47, v32

; #define PG8_STAGE(bufoff, gbase, voff) do { _Pragma("unroll") for (int _i = 0; _i < 2; ++_i) \
;         __builtin_amdgcn_global_load_lds((const unsigned*)((const char*)(gbase) + (voff)[_i]), (PG8_LAS unsigned*)(lds + (bufoff) + ldsw + _i * 8192), 16, 0, 0); } while (0)
; #define PG8_WAIT_V(n) asm volatile("s_waitcnt vmcnt(" #n ")" ::: "memory")
; #define PG8_BAR __builtin_amdgcn_s_barrier()
; template <class Epi, class Sched, bool ALIGN_EPI = false, bool SP2 = false>
; __device__ __forceinline__ void gemm_phase(PG8_LAS unsigned char* lds, const Gemm g, const Sched& S, const Epi& E) {
;     ...
;     f32x4 acc[2][2][4][2];
; #pragma unroll
;     for (int a = 0; a < 2; ++a)
; #pragma unroll
;         for (int b = 0; b < 2; ++b)
; #pragma unroll
;             for (int m = 0; m < 4; ++m)
; #pragma unroll
;                 for (int n = 0; n < 2; ++n) acc[a][b][m][n] = (f32x4){0.f, 0.f, 0.f, 0.f};
;     ...
;         PG8_WAIT_V(2); PG8_BAR;
;         PG8_STAGE(PG8_SB(1, 0), cB + kstep, voffB); PG8_STAGE(PG8_SA(1, 0), cA + kstep, voffA); PG8_STAGE(PG8_SB(1, 1), cB + hstep + kstep, voffB);
;         PG8_WAIT_V(6); PG8_BAR;
.LBB0_860:
	s_add_u32 s6, s10, 0x124c8000
	s_addc_u32 s7, s11, 0
	s_add_u32 s10, s10, 0x2d4c8000
	v_and_b32_e32 v9, 15, v8
	s_addc_u32 s11, s11, 0
	v_and_b32_e32 v10, 48, v8
	v_lshlrev_b32_e32 v9, 6, v9
	v_lshlrev_b32_e32 v8, 2, v8
	s_lshl_b32 s13, s13, 12
	s_add_i32 m0, s33, 0x18000
	v_lshl_add_u64 v[6:7], v[6:7], 0, s[50:51]
	v_or_b32_e32 v11, v9, v10
	s_lshl_b32 s20, s20, 13
	v_and_b32_e32 v8, 32, v8
	s_and_b32 s13, s13, 0x3000
	s_waitcnt vmcnt(2)
	s_barrier
	global_load_lds_dwordx4 v[6:7], off
	v_lshl_add_u64 v[4:5], v[4:5], 0, s[50:51]
	s_add_i32 m0, s33, 0x1a000
	s_add_i32 s49, s33, 0x8000
	s_add_i32 s53, s33, 0xa000
	v_bitop3_b32 v9, v9, v8, v10 bitop3:0x36
	v_bitop3_b32 v8, v11, s20, v8 bitop3:0xde
	global_load_lds_dwordx4 v[4:5], off
	v_lshl_add_u64 v[0:1], v[0:1], 0, s[50:51]
	s_mov_b32 m0, s49
	s_add_u32 s20, s40, 0x10080
	global_load_lds_dwordx4 v[0:1], off
	v_lshl_add_u64 v[0:1], v[2:3], 0, s[50:51]
	s_mov_b32 m0, s53
	s_addc_u32 s21, s41, 0
	global_load_lds_dwordx4 v[0:1], off
	s_add_i32 m0, s33, 0x1c000
	v_lshl_add_u64 v[0:1], s[20:21], 0, v[198:199]
	global_load_lds_dwordx4 v[0:1], off
	v_lshl_add_u64 v[0:1], s[20:21], 0, v[194:195]
	s_add_i32 m0, s33, 0x1e000
	v_mov_b32_e32 v116, 0
	global_load_lds_dwordx4 v[0:1], off
	s_waitcnt vmcnt(6)
	s_cmpk_lt_u32 s12, 0x100
	v_readlane_b32 s20, v254, 35
	v_or_b32_e32 v218, s13, v9
	s_mov_b32 s54, 1
	s_cselect_b64 s[12:13], -1, 0
	v_add_u32_e32 v219, 0, v8
	v_readlane_b32 s60, v254, 25
	s_mov_b32 s62, s20
	v_mov_b64_e32 v[0:1], 0
	v_mov_b64_e32 v[2:3], 0
	v_mov_b64_e32 v[4:5], 0
	v_mov_b64_e32 v[6:7], 0
	v_mov_b64_e32 v[8:9], 0
	v_mov_b64_e32 v[10:11], 0
	v_mov_b64_e32 v[12:13], 0
	v_mov_b64_e32 v[14:15], 0
	v_mov_b64_e32 v[16:17], 0
	v_mov_b64_e32 v[18:19], 0
	v_mov_b64_e32 v[20:21], 0
	v_mov_b64_e32 v[22:23], 0
	v_mov_b64_e32 v[24:25], 0
	v_mov_b64_e32 v[26:27], 0
	v_mov_b64_e32 v[28:29], 0
	v_mov_b64_e32 v[30:31], 0
	v_mov_b64_e32 v[32:33], 0
	v_mov_b64_e32 v[34:35], 0
	v_mov_b64_e32 v[36:37], 0
	v_mov_b64_e32 v[38:39], 0
	v_mov_b64_e32 v[40:41], 0
	v_mov_b64_e32 v[42:43], 0
	v_mov_b64_e32 v[44:45], 0
	v_mov_b64_e32 v[46:47], 0
	v_mov_b64_e32 v[48:49], 0
	v_mov_b64_e32 v[50:51], 0
	v_mov_b64_e32 v[52:53], 0
	v_mov_b64_e32 v[54:55], 0
	v_mov_b64_e32 v[56:57], 0
	v_mov_b64_e32 v[58:59], 0
	v_mov_b64_e32 v[60:61], 0
	v_mov_b64_e32 v[62:63], 0
	v_mov_b64_e32 v[64:65], 0
	v_mov_b64_e32 v[66:67], 0
	v_mov_b64_e32 v[68:69], 0
	v_mov_b64_e32 v[70:71], 0
	v_mov_b64_e32 v[72:73], 0
	v_mov_b64_e32 v[74:75], 0
	v_mov_b64_e32 v[76:77], 0
	v_mov_b64_e32 v[78:79], 0
	v_mov_b64_e32 v[80:81], 0
	v_mov_b64_e32 v[82:83], 0
	v_mov_b64_e32 v[84:85], 0
	v_mov_b64_e32 v[86:87], 0
	v_mov_b64_e32 v[88:89], 0
	v_mov_b64_e32 v[90:91], 0
	v_mov_b64_e32 v[92:93], 0
	v_mov_b64_e32 v[94:95], 0
	v_mov_b64_e32 v[96:97], 0
	v_mov_b64_e32 v[98:99], 0
	v_mov_b64_e32 v[100:101], 0
	v_mov_b64_e32 v[102:103], 0
	v_mov_b64_e32 v[104:105], 0
	v_mov_b64_e32 v[106:107], 0
	v_mov_b64_e32 v[108:109], 0
	v_mov_b64_e32 v[110:111], 0
	v_mov_b64_e32 v[112:113], 0
	v_mov_b64_e32 v[114:115], 0
	v_mov_b32_e32 v117, 0
	v_mov_b64_e32 v[118:119], 0
	v_mov_b64_e32 v[120:121], 0
	v_mov_b64_e32 v[122:123], 0
	v_mov_b64_e32 v[124:125], 0
	v_mov_b64_e32 v[126:127], 0
	s_barrier
	v_readlane_b32 s21, v254, 36
	s_branch .LBB0_863

; template <class Epi, class Sched, bool ALIGN_EPI = false, bool SP2 = false>
; __device__ __forceinline__ void gemm_phase(PG8_LAS unsigned char* lds, const Gemm g, const Sched& S, const Epi& E) {
;     ...
;         if (!has_next) break;
;         if (!Epi::KEEP_ACC || ((ui + 1) & 3) == 0) {
; #pragma unroll
;         for (int a = 0; a < 2; ++a)
; #pragma unroll
;             for (int b = 0; b < 2; ++b)
; #pragma unroll
;                 for (int m = 0; m < 4; ++m)
; #pragma unroll
;                     for (int n = 0; n < 2; ++n) acc[a][b][m][n] = (f32x4){0.f, 0.f, 0.f, 0.f};
;         }
;         cur = nxt; cA = nA; cB = nB; ++ui;
.LBB0_934:
	v_mov_b64_e32 v[0:1], 0
	v_mov_b64_e32 v[2:3], 0
	v_mov_b64_e32 v[4:5], 0
	v_mov_b64_e32 v[6:7], 0
	v_mov_b64_e32 v[8:9], 0
	v_mov_b64_e32 v[10:11], 0
	v_mov_b64_e32 v[12:13], 0
	v_mov_b64_e32 v[14:15], 0
	v_mov_b64_e32 v[16:17], 0
	v_mov_b64_e32 v[18:19], 0
	v_mov_b64_e32 v[20:21], 0
	v_mov_b64_e32 v[22:23], 0
	v_mov_b64_e32 v[24:25], 0
	v_mov_b64_e32 v[26:27], 0
	v_mov_b64_e32 v[28:29], 0
	v_mov_b64_e32 v[30:31], 0
	v_mov_b64_e32 v[32:33], 0
	v_mov_b64_e32 v[34:35], 0
	v_mov_b64_e32 v[36:37], 0
	v_mov_b64_e32 v[38:39], 0
	v_mov_b64_e32 v[40:41], 0
	v_mov_b64_e32 v[42:43], 0
	v_mov_b64_e32 v[44:45], 0
	v_mov_b64_e32 v[46:47], 0
	v_mov_b64_e32 v[48:49], 0
	v_mov_b64_e32 v[50:51], 0
	v_mov_b64_e32 v[52:53], 0
	v_mov_b64_e32 v[54:55], 0
	v_mov_b64_e32 v[56:57], 0
	v_mov_b64_e32 v[58:59], 0
	v_mov_b64_e32 v[60:61], 0
	v_mov_b64_e32 v[62:63], 0
	v_mov_b64_e32 v[64:65], 0
	v_mov_b64_e32 v[66:67], 0
	v_mov_b64_e32 v[68:69], 0
	v_mov_b64_e32 v[70:71], 0
	v_mov_b64_e32 v[72:73], 0
	v_mov_b64_e32 v[74:75], 0
	v_mov_b64_e32 v[76:77], 0
	v_mov_b64_e32 v[78:79], 0
	v_mov_b64_e32 v[80:81], 0
	v_mov_b64_e32 v[82:83], 0
	v_mov_b64_e32 v[84:85], 0
	v_mov_b64_e32 v[86:87], 0
	v_mov_b64_e32 v[88:89], 0
	v_mov_b64_e32 v[90:91], 0
	v_mov_b64_e32 v[92:93], 0
	v_mov_b64_e32 v[94:95], 0
	v_mov_b64_e32 v[96:97], 0
	v_mov_b64_e32 v[98:99], 0
	v_mov_b64_e32 v[100:101], 0
	v_mov_b64_e32 v[102:103], 0
	v_mov_b64_e32 v[104:105], 0
	v_mov_b64_e32 v[106:107], 0
	v_mov_b64_e32 v[108:109], 0
	v_mov_b64_e32 v[110:111], 0
	v_mov_b64_e32 v[112:113], 0
	v_mov_b64_e32 v[114:115], 0
	v_mov_b64_e32 v[116:117], 0
	v_mov_b64_e32 v[118:119], 0
	v_mov_b64_e32 v[120:121], 0
	v_mov_b64_e32 v[122:123], 0
	v_mov_b64_e32 v[124:125], 0
	v_mov_b64_e32 v[126:127], 0
	s_andn2_b64 vcc, exec, s[4:5]
	s_cbranch_vccnz .LBB0_861

;     __device__ bool next(int i, Unit& u) const { const int tl = (i >> 2) * G + c; if (tl >= nM * 4) return false; const int sub = i & 3; u.pm = sub * nM + (tl >> 2); u.pn = sub * 4 + (tl & 3); return true; }
; template <class Epi, class Sched, bool ALIGN_EPI = false, bool SP2 = false>
; __device__ __forceinline__ void gemm_phase(PG8_LAS unsigned char* lds, const Gemm g, const Sched& S, const Epi& E) {
;     ...
;     f32x4 acc[2][2][4][2];
; #pragma unroll
;     for (int a = 0; a < 2; ++a)
; #pragma unroll
;         for (int b = 0; b < 2; ++b)
; #pragma unroll
;             for (int m = 0; m < 4; ++m)
; #pragma unroll
;                 for (int n = 0; n < 2; ++n) acc[a][b][m][n] = (f32x4){0.f, 0.f, 0.f, 0.f};
;     ...
;         const bool has_next = S.next(ui + 1, nxt);
;         const char* nA = has_next ? (const char*)g.A + (size_t)nxt.pm * tstep : cA; const char* nB = has_next ? (const char*)g.Bt + (size_t)nxt.pn * tstep : cB;
;         for (int t = 0; t < nt; t += 2) {
;             const bool last = (t == nt - 2);
;             const char* a1 = cA + (size_t)(t + 1) * kstep;
;             const char* a2 = last ? nA : cA + (size_t)(t + 2) * kstep; const char* b2 = last ? nB : cB + (size_t)(t + 2) * kstep;
;             const char* a3 = a2 + kstep; const char* b3 = b2 + kstep;
.LBB0_1004:
	s_ashr_i32 s35, s34, 31
	s_lshl_b64 s[8:9], s[34:35], 19
	s_add_u32 s36, s4, s8
	s_addc_u32 s37, s5, s9
	s_and_b64 s[8:9], s[40:41], exec
	s_cselect_b32 s8, s37, s69
	s_cselect_b32 s9, s36, s68
	s_ashr_i32 s29, s28, 31
	s_lshl_b64 s[42:43], s[28:29], 19
	s_add_u32 s42, s6, s42
	s_addc_u32 s43, s7, s43
	s_and_b64 s[70:71], s[40:41], exec
	s_cselect_b32 s16, s43, s49
	s_cselect_b32 s29, s42, s48
	s_add_u32 s35, s48, 0x100
	s_addc_u32 s45, s49, 0
	s_add_u32 s48, s68, 0x40080
	v_mov_b32_e32 v0, 0
	s_addc_u32 s49, s69, 0
	s_mov_b32 s66, -2
	v_mov_b32_e32 v1, 0
	v_mov_b64_e32 v[2:3], 0
	v_mov_b64_e32 v[4:5], 0
	v_mov_b64_e32 v[6:7], 0
	v_mov_b64_e32 v[8:9], 0
	v_mov_b64_e32 v[10:11], 0
	v_mov_b64_e32 v[12:13], 0
	v_mov_b64_e32 v[14:15], 0
	v_mov_b64_e32 v[16:17], 0
	v_mov_b64_e32 v[18:19], 0
	v_mov_b64_e32 v[20:21], 0
	v_mov_b64_e32 v[22:23], 0
	v_mov_b64_e32 v[24:25], 0
	v_mov_b64_e32 v[26:27], 0
	v_mov_b64_e32 v[28:29], 0
	v_mov_b64_e32 v[30:31], 0
	v_mov_b64_e32 v[32:33], 0
	v_mov_b64_e32 v[34:35], 0
	v_mov_b64_e32 v[36:37], 0
	v_mov_b64_e32 v[38:39], 0
	v_mov_b64_e32 v[40:41], 0
	v_mov_b64_e32 v[42:43], 0
	v_mov_b64_e32 v[44:45], 0
	v_mov_b64_e32 v[46:47], 0
	v_mov_b64_e32 v[48:49], 0
	v_mov_b64_e32 v[50:51], 0
	v_mov_b64_e32 v[52:53], 0
	v_mov_b64_e32 v[54:55], 0
	v_mov_b64_e32 v[56:57], 0
	v_mov_b64_e32 v[58:59], 0
	v_mov_b64_e32 v[60:61], 0
	v_mov_b64_e32 v[62:63], 0
	v_mov_b64_e32 v[64:65], 0
	v_mov_b64_e32 v[66:67], 0
	v_mov_b64_e32 v[68:69], 0
	v_mov_b64_e32 v[70:71], 0
	v_mov_b64_e32 v[72:73], 0
	v_mov_b64_e32 v[74:75], 0
	v_mov_b64_e32 v[76:77], 0
	v_mov_b64_e32 v[78:79], 0
	v_mov_b64_e32 v[80:81], 0
	v_mov_b64_e32 v[82:83], 0
	v_mov_b64_e32 v[84:85], 0
	v_mov_b64_e32 v[86:87], 0
	v_mov_b64_e32 v[88:89], 0
	v_mov_b64_e32 v[90:91], 0
	v_mov_b64_e32 v[92:93], 0
	v_mov_b64_e32 v[94:95], 0
	v_mov_b64_e32 v[96:97], 0
	v_mov_b64_e32 v[98:99], 0
	v_mov_b64_e32 v[104:105], 0
	v_mov_b64_e32 v[106:107], 0
	v_mov_b64_e32 v[120:121], 0
	v_mov_b64_e32 v[122:123], 0
	v_mov_b64_e32 v[124:125], 0
	v_mov_b64_e32 v[126:127], 0
	v_mov_b64_e32 v[132:133], 0
	v_mov_b64_e32 v[134:135], 0
	v_mov_b64_e32 v[140:141], 0
	v_mov_b64_e32 v[142:143], 0
	v_mov_b64_e32 v[148:149], 0
	v_mov_b64_e32 v[150:151], 0
	v_mov_b64_e32 v[152:153], 0
	v_mov_b64_e32 v[154:155], 0

;     __device__ bool next(int i, Unit& u) const { const int tl = (i >> 2) * G + c; if (tl >= nM * 4) return false; const int sub = i & 3; u.pm = sub * nM + (tl >> 2); u.pn = sub * 4 + (tl & 3); return true; }
; template <class Epi, class Sched, bool ALIGN_EPI = false, bool SP2 = false>
; __device__ __forceinline__ void gemm_phase(PG8_LAS unsigned char* lds, const Gemm g, const Sched& S, const Epi& E) {
;     ...
;     f32x4 acc[2][2][4][2];
; #pragma unroll
;     for (int a = 0; a < 2; ++a)
; #pragma unroll
;         for (int b = 0; b < 2; ++b)
; #pragma unroll
;             for (int m = 0; m < 4; ++m)
; #pragma unroll
;                 for (int n = 0; n < 2; ++n) acc[a][b][m][n] = (f32x4){0.f, 0.f, 0.f, 0.f};
;     ...
;         const bool has_next = S.next(ui + 1, nxt);
;         const char* nA = has_next ? (const char*)g.A + (size_t)nxt.pm * tstep : cA; const char* nB = has_next ? (const char*)g.Bt + (size_t)nxt.pn * tstep : cB;
;         for (int t = 0; t < nt; t += 2) {
;             const bool last = (t == nt - 2);
;             const char* a1 = cA + (size_t)(t + 1) * kstep;
;             const char* a2 = last ? nA : cA + (size_t)(t + 2) * kstep; const char* b2 = last ? nB : cB + (size_t)(t + 2) * kstep;
;             const char* a3 = a2 + kstep; const char* b3 = b2 + kstep;
.LBB0_1095:
	s_ashr_i32 s77, s76, 31
	s_lshl_b64 s[4:5], s[76:77], 19
	s_add_u32 s12, s18, s4
	s_addc_u32 s13, s19, s5
	s_and_b64 s[4:5], s[38:39], exec
	s_cselect_b32 s8, s13, s47
	s_cselect_b32 s9, s12, s46
	s_ashr_i32 s29, s28, 31
	s_lshl_b64 s[4:5], s[28:29], 19
	s_add_u32 s4, s34, s4
	s_addc_u32 s5, s35, s5
	s_and_b64 s[90:91], s[38:39], exec
	s_cselect_b32 s29, s5, s45
	s_cselect_b32 s41, s4, s44
	s_add_u32 s43, s44, 0x100
	s_addc_u32 s77, s45, 0
	s_add_u32 s44, s46, 0x40080
	v_mov_b32_e32 v8, 0
	s_mov_b32 s73, s94
	s_mov_b32 s70, s93
	s_addc_u32 s45, s47, 0
	s_mov_b32 s90, -2
	v_mov_b64_e32 v[0:1], 0
	v_mov_b64_e32 v[2:3], 0
	v_mov_b64_e32 v[4:5], 0
	v_mov_b64_e32 v[6:7], 0
	v_mov_b32_e32 v9, 0
	v_mov_b64_e32 v[10:11], 0
	v_mov_b64_e32 v[12:13], 0
	v_mov_b64_e32 v[14:15], 0
	v_mov_b64_e32 v[16:17], 0
	v_mov_b64_e32 v[18:19], 0
	v_mov_b64_e32 v[20:21], 0
	v_mov_b64_e32 v[22:23], 0
	v_mov_b64_e32 v[24:25], 0
	v_mov_b64_e32 v[26:27], 0
	v_mov_b64_e32 v[28:29], 0
	v_mov_b64_e32 v[30:31], 0
	v_mov_b64_e32 v[32:33], 0
	v_mov_b64_e32 v[34:35], 0
	v_mov_b64_e32 v[36:37], 0
	v_mov_b64_e32 v[38:39], 0
	v_mov_b64_e32 v[40:41], 0
	v_mov_b64_e32 v[42:43], 0
	v_mov_b64_e32 v[44:45], 0
	v_mov_b64_e32 v[46:47], 0
	v_mov_b64_e32 v[48:49], 0
	v_mov_b64_e32 v[50:51], 0
	v_mov_b64_e32 v[52:53], 0
	v_mov_b64_e32 v[54:55], 0
	v_mov_b64_e32 v[56:57], 0
	v_mov_b64_e32 v[58:59], 0
	v_mov_b64_e32 v[60:61], 0
	v_mov_b64_e32 v[62:63], 0
	v_mov_b64_e32 v[88:89], 0
	v_mov_b64_e32 v[90:91], 0
	v_mov_b64_e32 v[100:101], 0
	v_mov_b64_e32 v[102:103], 0
	v_mov_b64_e32 v[104:105], 0
	v_mov_b64_e32 v[106:107], 0
	v_mov_b64_e32 v[108:109], 0
	v_mov_b64_e32 v[110:111], 0
	v_mov_b64_e32 v[112:113], 0
	v_mov_b64_e32 v[114:115], 0
	v_mov_b64_e32 v[116:117], 0
	v_mov_b64_e32 v[118:119], 0
	v_mov_b64_e32 v[120:121], 0
	v_mov_b64_e32 v[122:123], 0
	v_mov_b64_e32 v[124:125], 0
	v_mov_b64_e32 v[126:127], 0
	v_mov_b64_e32 v[128:129], 0
	v_mov_b64_e32 v[130:131], 0
	v_mov_b64_e32 v[132:133], 0
	v_mov_b64_e32 v[134:135], 0
	v_mov_b64_e32 v[136:137], 0
	v_mov_b64_e32 v[138:139], 0
	v_mov_b64_e32 v[140:141], 0
	v_mov_b64_e32 v[142:143], 0
	v_mov_b64_e32 v[144:145], 0
	v_mov_b64_e32 v[146:147], 0
	v_mov_b64_e32 v[148:149], 0
	v_mov_b64_e32 v[150:151], 0
	v_mov_b64_e32 v[152:153], 0
	v_mov_b64_e32 v[154:155], 0
	v_mov_b64_e32 v[156:157], 0
	v_mov_b64_e32 v[158:159], 0

; template <class Epi, class Sched, bool ALIGN_EPI = false, bool SP2 = false>
; __device__ __forceinline__ void gemm_phase(PG8_LAS unsigned char* lds, const Gemm g, const Sched& S, const Epi& E) {
;     ...
;     f32x4 acc[2][2][4][2];
; #pragma unroll
;     for (int a = 0; a < 2; ++a)
; #pragma unroll
;         for (int b = 0; b < 2; ++b)
; #pragma unroll
;             for (int m = 0; m < 4; ++m)
; #pragma unroll
;                 for (int n = 0; n < 2; ++n) acc[a][b][m][n] = (f32x4){0.f, 0.f, 0.f, 0.f};
;     ...
;         const char* nA = has_next ? (const char*)g.A + (size_t)nxt.pm * tstep : cA; const char* nB = has_next ? (const char*)g.Bt + (size_t)nxt.pn * tstep : cB;
;         for (int t = 0; t < nt; t += 2) {
;             const bool last = (t == nt - 2);
;             const char* a1 = cA + (size_t)(t + 1) * kstep;
;             const char* a2 = last ? nA : cA + (size_t)(t + 2) * kstep; const char* b2 = last ? nB : cB + (size_t)(t + 2) * kstep;
;             const char* a3 = a2 + kstep; const char* b3 = b2 + kstep;
.LBB0_1250:
	s_add_u32 s8, s42, 0x100
	v_mov_b32_e32 v0, 0
	s_addc_u32 s9, s43, 0
	s_mov_b32 s66, -2
	v_mov_b32_e32 v1, 0
	v_mov_b64_e32 v[2:3], 0
	v_mov_b64_e32 v[4:5], 0
	v_mov_b64_e32 v[6:7], 0
	v_mov_b64_e32 v[8:9], 0
	v_mov_b64_e32 v[10:11], 0
	v_mov_b64_e32 v[12:13], 0
	v_mov_b64_e32 v[14:15], 0
	v_mov_b64_e32 v[16:17], 0
	v_mov_b64_e32 v[18:19], 0
	v_mov_b64_e32 v[20:21], 0
	v_mov_b64_e32 v[22:23], 0
	v_mov_b64_e32 v[24:25], 0
	v_mov_b64_e32 v[26:27], 0
	v_mov_b64_e32 v[28:29], 0
	v_mov_b64_e32 v[30:31], 0
	v_mov_b64_e32 v[32:33], 0
	v_mov_b64_e32 v[34:35], 0
	v_mov_b64_e32 v[36:37], 0
	v_mov_b64_e32 v[38:39], 0
	v_mov_b64_e32 v[40:41], 0
	v_mov_b64_e32 v[42:43], 0
	v_mov_b64_e32 v[44:45], 0
	v_mov_b64_e32 v[46:47], 0
	v_mov_b64_e32 v[48:49], 0
	v_mov_b64_e32 v[50:51], 0
	v_mov_b64_e32 v[52:53], 0
	v_mov_b64_e32 v[54:55], 0
	v_mov_b64_e32 v[56:57], 0
	v_mov_b64_e32 v[58:59], 0
	v_mov_b64_e32 v[60:61], 0
	v_mov_b64_e32 v[62:63], 0
	v_mov_b64_e32 v[64:65], 0
	v_mov_b64_e32 v[66:67], 0
	v_mov_b64_e32 v[68:69], 0
	v_mov_b64_e32 v[70:71], 0
	v_mov_b64_e32 v[72:73], 0
	v_mov_b64_e32 v[74:75], 0
	v_mov_b64_e32 v[76:77], 0
	v_mov_b64_e32 v[78:79], 0
	v_mov_b64_e32 v[80:81], 0
	v_mov_b64_e32 v[82:83], 0
	v_mov_b64_e32 v[84:85], 0
	v_mov_b64_e32 v[86:87], 0
	v_mov_b64_e32 v[88:89], 0
	v_mov_b64_e32 v[90:91], 0
	v_mov_b64_e32 v[92:93], 0
	v_mov_b64_e32 v[94:95], 0
	v_mov_b64_e32 v[96:97], 0
	v_mov_b64_e32 v[98:99], 0
	v_mov_b64_e32 v[104:105], 0
	v_mov_b64_e32 v[106:107], 0
	v_mov_b64_e32 v[120:121], 0
	v_mov_b64_e32 v[122:123], 0
	v_mov_b64_e32 v[124:125], 0
	v_mov_b64_e32 v[126:127], 0
	v_mov_b64_e32 v[132:133], 0
	v_mov_b64_e32 v[134:135], 0
	v_mov_b64_e32 v[140:141], 0
	v_mov_b64_e32 v[142:143], 0
	v_mov_b64_e32 v[148:149], 0
	v_mov_b64_e32 v[150:151], 0
	v_mov_b64_e32 v[156:157], 0
	v_mov_b64_e32 v[158:159], 0
